# gMLP step C: the four MFMA loops software-pipelined (double-buffered LDS operand reads one iteration ahead, counted lgkmcnt) on the workgroup class the probes showed critical in P2
# speedup vs baseline: 1.0058x; 1.0058x over previous
; #define LAS __attribute__((address_space(3)))
; #define MFMA32(a, b, c) __builtin_amdgcn_mfma_f32_32x32x16_bf16((a), (b), (c), 0, 0, 0)
; __device__ __forceinline__ void gmlp_task(LAS unsigned char* lds, const Params& p, const bf16_t* P, bf16_t* Y, const float* svg, float* ssb, int l, bool sample, int b, int g, int q, int tid, int wave, int lane, bool load_ws = true) {
;     ...
; #pragma unroll
;             for (int pr = 0; pr < 2; ++pr) { uw[pr] = *(const u32x4*)(up + 16 * pr); gw[pr] = *(const u32x4*)(gp + 16 * pr); }
;             f32x16 acc;
; #pragma unroll
;             for (int e = 0; e < 16; ++e) acc[e] = 0.f;
;             const LAS bf16_t* tr = VGT + (8 * h + ((lane & 15) >> 2)) * 72 + 32 * dt + 16 * ((lane >> 4) & 1) + 4 * (lane & 3);
;             for (int ks = 0; ks < nks; ++ks) {
;                 const s16x4 alo = __builtin_amdgcn_ds_read_tr16_b64_v4i16((LAS s16x4*)(tr + 16 * ks * 72)), ahi = __builtin_amdgcn_ds_read_tr16_b64_v4i16((LAS s16x4*)(tr + (16 * ks + 4) * 72));
;                 const bf16x8 a = __builtin_shufflevector(alo, ahi, 0, 1, 2, 3, 4, 5, 6, 7);
;                 const bf16x8 bw = *(const LAS bf16x8*)(WSL + (32 * it + r) * 136 + 16 * ks + 8 * h);
;                 acc = MFMA32(a, bw, acc);
;             }
.LBB0_488:
	s_or_b64 exec, exec, s[16:17]
	v_and_b32_e32 v10, 31, v42
	v_readlane_b32 s4, v253, 39
	s_lshl_b32 s11, s33, 7
	s_add_i32 s11, s11, s22
	v_or_b32_e32 v38, s4, v10
	v_add_u32_e32 v2, s11, v38
	v_ashrrev_i32_e32 v3, 31, v2
	v_lshl_add_u64 v[2:3], v[2:3], 2, s[64:65]
	s_waitcnt lgkmcnt(0)
	s_barrier
	global_load_dword v36, v[2:3], off
	v_add_u32_e32 v0, s44, v38
	v_mov_b64_e32 v[2:3], s[68:69]
	v_ashrrev_i32_e32 v11, 2, v42
	v_mad_u64_u32 v[2:3], s[16:17], v0, s73, v[2:3]
	v_readlane_b32 s4, v253, 40
	v_and_b32_e32 v34, -8, v11
	s_lshl_b32 s44, s4, 1
	v_lshl_add_u64 v[2:3], s[0:1], 1, v[2:3]
	v_ashrrev_i32_e32 v35, 31, v34
	v_lshl_add_u64 v[2:3], v[2:3], 0, s[44:45]
	v_lshl_add_u64 v[2:3], v[34:35], 1, v[2:3]
	s_mov_b64 s[4:5], 0x1400
	v_lshl_add_u64 v[4:5], v[2:3], 0, s[4:5]
	s_mov_b64 s[4:5], 0x2400
	v_lshl_add_u64 v[6:7], v[2:3], 0, s[4:5]
	s_movk_i32 s4, 0x1000
	v_add_co_u32_e32 v8, vcc, s4, v2
	s_movk_i32 s4, 0x2000
	s_nop 0
	v_addc_co_u32_e32 v9, vcc, 0, v3, vcc
	v_add_co_u32_e32 v2, vcc, s4, v2
	v_readlane_b32 s4, v254, 55
	s_nop 0
	v_addc_co_u32_e32 v3, vcc, 0, v3, vcc
	global_load_dwordx4 v[30:33], v[8:9], off offset:1024
	global_load_dwordx4 v[26:29], v[2:3], off offset:1024
	global_load_dwordx4 v[22:25], v[4:5], off offset:32
	global_load_dwordx4 v[18:21], v[6:7], off offset:32
	v_add_u32_e32 v132, s14, v38
	v_mov_b64_e32 v[134:135], s[68:69]
	v_mad_u64_u32 v[134:135], vcc, v132, s73, v[134:135]
	v_lshl_add_u64 v[134:135], s[0:1], 1, v[134:135]
	v_lshl_add_u64 v[134:135], v[134:135], 0, s[44:45]
	v_lshl_add_u64 v[134:135], v[34:35], 1, v[134:135]
	s_mov_b64 s[16:17], 0x1000
	v_lshl_add_u64 v[136:137], v[134:135], 0, s[16:17]
	s_mov_b64 s[16:17], 0x2000
	v_lshl_add_u64 v[138:139], v[134:135], 0, s[16:17]
	s_mov_b64 s[16:17], 0x1400
	v_lshl_add_u64 v[140:141], v[134:135], 0, s[16:17]
	s_mov_b64 s[16:17], 0x2400
	v_lshl_add_u64 v[142:143], v[134:135], 0, s[16:17]
	global_load_dwordx4 v[80:83], v[136:137], off offset:1024
	global_load_dwordx4 v[76:79], v[138:139], off offset:1024
	global_load_dwordx4 v[72:75], v[140:141], off offset:32
	global_load_dwordx4 v[68:71], v[142:143], off offset:32
	v_add_u32_e32 v132, s12, v38
	v_mov_b64_e32 v[134:135], s[68:69]
	v_mad_u64_u32 v[134:135], vcc, v132, s73, v[134:135]
	v_lshl_add_u64 v[134:135], s[0:1], 1, v[134:135]
	v_lshl_add_u64 v[134:135], v[134:135], 0, s[44:45]
	v_lshl_add_u64 v[134:135], v[34:35], 1, v[134:135]
	s_mov_b64 s[16:17], 0x1000
	v_lshl_add_u64 v[136:137], v[134:135], 0, s[16:17]
	s_mov_b64 s[16:17], 0x2000
	v_lshl_add_u64 v[138:139], v[134:135], 0, s[16:17]
	s_mov_b64 s[16:17], 0x1400
	v_lshl_add_u64 v[140:141], v[134:135], 0, s[16:17]
	s_mov_b64 s[16:17], 0x2400
	v_lshl_add_u64 v[142:143], v[134:135], 0, s[16:17]
	global_load_dwordx4 v[96:99], v[136:137], off offset:1024
	global_load_dwordx4 v[92:95], v[138:139], off offset:1024
	global_load_dwordx4 v[88:91], v[140:141], off offset:32
	global_load_dwordx4 v[84:87], v[142:143], off offset:32
	v_add_u32_e32 v132, s10, v38
	v_mov_b64_e32 v[134:135], s[68:69]
	v_mad_u64_u32 v[134:135], vcc, v132, s73, v[134:135]
	v_lshl_add_u64 v[134:135], s[0:1], 1, v[134:135]
	v_lshl_add_u64 v[134:135], v[134:135], 0, s[44:45]
	v_lshl_add_u64 v[134:135], v[34:35], 1, v[134:135]
	s_mov_b64 s[16:17], 0x1000
	v_lshl_add_u64 v[136:137], v[134:135], 0, s[16:17]
	s_mov_b64 s[16:17], 0x2000
	v_lshl_add_u64 v[138:139], v[134:135], 0, s[16:17]
	s_mov_b64 s[16:17], 0x1400
	v_lshl_add_u64 v[140:141], v[134:135], 0, s[16:17]
	s_mov_b64 s[16:17], 0x2400
	v_lshl_add_u64 v[142:143], v[134:135], 0, s[16:17]
	global_load_dwordx4 v[112:115], v[136:137], off offset:1024
	global_load_dwordx4 v[108:111], v[138:139], off offset:1024
	global_load_dwordx4 v[104:107], v[140:141], off offset:32
	global_load_dwordx4 v[100:103], v[142:143], off offset:32
	v_lshrrev_b32_e32 v4, 3, v11
	v_mul_u32_u24_e32 v3, 0x110, v10
	v_lshlrev_b32_e32 v5, 4, v4
	s_movk_i32 s11, 0x480
	v_bfe_u32 v2, v42, 2, 2
	v_add3_u32 v37, v3, v5, s4
	v_mul_lo_u32 v3, v4, s11
	v_mad_u32_u24 v2, v2, s89, v3
	v_lshlrev_b32_e32 v3, 1, v42
	v_and_b32_e32 v3, 32, v3
	v_lshlrev_b32_e32 v4, 3, v45
	v_add3_u32 v39, v2, v3, v4
	v_readlane_b32 s4, v254, 58
	v_mov_b32_e32 v2, 0
	v_mov_b32_e32 v41, v37
	v_add_u32_e32 v40, s4, v39
	s_mov_b32 s11, s77
	v_mov_b32_e32 v3, v2
	v_mov_b32_e32 v4, v2
	v_mov_b32_e32 v5, v2
	v_mov_b32_e32 v6, v2
	v_mov_b32_e32 v7, v2
	v_mov_b32_e32 v8, v2
	v_mov_b32_e32 v9, v2
	v_mov_b32_e32 v10, v2
	v_mov_b32_e32 v11, v2
	v_mov_b32_e32 v12, v2
	v_mov_b32_e32 v13, v2
	v_mov_b32_e32 v14, v2
	v_mov_b32_e32 v15, v2
	v_mov_b32_e32 v16, v2
	v_mov_b32_e32 v17, v2
	ds_read_b64_tr_b16 v[44:45], v40
	ds_read_b64_tr_b16 v[46:47], v40 offset:576
	ds_read_b128 v[48:51], v41
.Lmy_c489_loop:
	ds_read_b64_tr_b16 v[116:117], v40 offset:2304
	ds_read_b64_tr_b16 v[118:119], v40 offset:2880
	ds_read_b128 v[120:123], v41 offset:32
	s_add_i32 s11, s11, -2
	v_add_u32_e32 v41, 64, v41
	v_add_u32_e32 v40, 0x1200, v40
	s_cmp_eq_u32 s11, 0
	s_waitcnt lgkmcnt(3)
	v_mfma_f32_32x32x16_bf16 v[2:17], v[44:47], v[48:51], v[2:17]
	s_cbranch_scc1 .Lmy_c489_tail
	ds_read_b64_tr_b16 v[44:45], v40
	ds_read_b64_tr_b16 v[46:47], v40 offset:576
	ds_read_b128 v[48:51], v41
	s_waitcnt lgkmcnt(3)
	v_mfma_f32_32x32x16_bf16 v[2:17], v[116:119], v[120:123], v[2:17]
	s_branch .Lmy_c489_loop
; #define LAS __attribute__((address_space(3)))
; __device__ __forceinline__ unsigned pk2(float lo, float hi) { const f32x2 v = {lo, hi}; return __builtin_bit_cast(unsigned, __builtin_convertvector(v, bf16x2_t)); }
; __device__ __forceinline__ void gmlp_task(LAS unsigned char* lds, const Params& p, const bf16_t* P, bf16_t* Y, const float* svg, float* ssb, int l, bool sample, int b, int g, int q, int tid, int wave, int lane, bool load_ws = true) {
;     ...
; #pragma unroll
;             for (int pr = 0; pr < 2; ++pr) { uw[pr] = *(const u32x4*)(up + 16 * pr); gw[pr] = *(const u32x4*)(gp + 16 * pr); }
;             f32x16 acc;
; #pragma unroll
;             for (int e = 0; e < 16; ++e) acc[e] = 0.f;
;             const LAS bf16_t* tr = VGT + (8 * h + ((lane & 15) >> 2)) * 72 + 32 * dt + 16 * ((lane >> 4) & 1) + 4 * (lane & 3);
;             for (int ks = 0; ks < nks; ++ks) {
;                 const s16x4 alo = __builtin_amdgcn_ds_read_tr16_b64_v4i16((LAS s16x4*)(tr + 16 * ks * 72)), ahi = __builtin_amdgcn_ds_read_tr16_b64_v4i16((LAS s16x4*)(tr + (16 * ks + 4) * 72));
;     ...
;             bf16_t* yp = Y + row * DM + 1024 + g * 64 + 32 * dt + 8 * h;
;             float ss = 0.f;
; #pragma unroll
;             for (int pr = 0; pr < 2; ++pr) {
;                 float a[4], bq[4];
; #pragma unroll
;                 for (int k = 0; k < 4; ++k) { a[k] = acc[8 * pr + k] + bias; bq[k] = acc[8 * pr + 4 + k] + bias; }
; #pragma unroll
;                 for (int k = 0; k < 4; ++k) swap_halves(a[k], bq[k]);
;                 const u32x4 u4 = uw[pr], g4 = gw[pr];
;                 a[0] *= bf_lo(u4.x); a[1] *= bf_hi(u4.x); a[2] *= bf_lo(u4.y); a[3] *= bf_hi(u4.y); bq[0] *= bf_lo(u4.z); bq[1] *= bf_hi(u4.z); bq[2] *= bf_lo(u4.w); bq[3] *= bf_hi(u4.w);
;                 ss += ((a[0] * a[0] + a[1] * a[1]) + (a[2] * a[2] + a[3] * a[3])) + ((bq[0] * bq[0] + bq[1] * bq[1]) + (bq[2] * bq[2] + bq[3] * bq[3]));
;                 u32x4 w; w.x = pk2(a[0] * bf_lo(g4.x), a[1] * bf_hi(g4.x)); w.y = pk2(a[2] * bf_lo(g4.y), a[3] * bf_hi(g4.y));
;                 w.z = pk2(bq[0] * bf_lo(g4.z), bq[1] * bf_hi(g4.z)); w.w = pk2(bq[2] * bf_lo(g4.w), bq[3] * bf_hi(g4.w));
;                 *(u32x4*)(yp + 16 * pr) = w;
;             }
;             ss += __shfl_xor(ss, 32);
;             if (h == 0) ssb[row * 32 + g * 2 + dt] = ss;
.Lmy_c489_tail:
	s_waitcnt lgkmcnt(0)
	v_mfma_f32_32x32x16_bf16 v[2:17], v[116:119], v[120:123], v[2:17]
	v_lshlrev_b64 v[40:41], 12, v[0:1]
	v_lshl_add_u64 v[40:41], s[36:37], 0, v[40:41]
	v_lshl_add_u64 v[40:41], s[0:1], 1, v[40:41]
	s_waitcnt vmcnt(16)
	s_nop 6
	v_add_f32_e32 v2, v36, v2
	v_add_f32_e32 v6, v36, v6
	v_add_f32_e32 v3, v36, v3
	v_add_f32_e32 v7, v36, v7
	v_add_f32_e32 v4, v36, v4
	v_add_f32_e32 v8, v36, v8
	v_add_f32_e32 v5, v36, v5
	v_add_f32_e32 v9, v36, v9
	v_lshl_add_u64 v[40:41], v[40:41], 0, s[44:45]
	v_permlane32_swap_b32_e32 v2, v6
	v_permlane32_swap_b32_e32 v3, v7
	v_permlane32_swap_b32_e32 v4, v8
	v_permlane32_swap_b32_e32 v5, v9
	v_cmp_gt_u32_e64 s[40:41], 32, v42
	v_lshl_add_u64 v[42:43], v[34:35], 1, v[40:41]
	s_waitcnt vmcnt(15)
	v_lshlrev_b32_e32 v40, 16, v30
	v_and_b32_e32 v41, 0xffff0000, v30
	v_lshlrev_b32_e32 v30, 16, v31
	v_and_b32_e32 v31, 0xffff0000, v31
	v_pk_mul_f32 v[2:3], v[40:41], v[2:3]
	s_waitcnt vmcnt(14)
	v_lshlrev_b32_e32 v44, 16, v26
	v_and_b32_e32 v45, 0xffff0000, v26
	v_pk_mul_f32 v[4:5], v[30:31], v[4:5]
	v_lshlrev_b32_e32 v26, 16, v27
	v_and_b32_e32 v27, 0xffff0000, v27
	v_pk_mul_f32 v[40:41], v[2:3], v[2:3]
	v_pk_mul_f32 v[2:3], v[2:3], v[44:45]
	v_pk_mul_f32 v[30:31], v[4:5], v[4:5]
	v_pk_mul_f32 v[4:5], v[4:5], v[26:27]
	v_cvt_pk_bf16_f32 v2, v2, v3
	v_cvt_pk_bf16_f32 v3, v4, v5
	v_lshlrev_b32_e32 v4, 16, v32
	v_and_b32_e32 v5, 0xffff0000, v32
	v_pk_mul_f32 v[4:5], v[4:5], v[6:7]
	v_lshlrev_b32_e32 v6, 16, v28
	v_and_b32_e32 v7, 0xffff0000, v28
	v_pk_mul_f32 v[26:27], v[4:5], v[4:5]
	v_pk_mul_f32 v[4:5], v[4:5], v[6:7]
	v_lshlrev_b32_e32 v6, 16, v33
	v_and_b32_e32 v7, 0xffff0000, v33
	v_pk_mul_f32 v[6:7], v[6:7], v[8:9]
	v_lshlrev_b32_e32 v28, 16, v29
	v_and_b32_e32 v29, 0xffff0000, v29
	v_pk_mul_f32 v[8:9], v[6:7], v[6:7]
	v_pk_mul_f32 v[6:7], v[6:7], v[28:29]
	v_cvt_pk_bf16_f32 v4, v4, v5
	v_cvt_pk_bf16_f32 v5, v6, v7
	global_store_dwordx4 v[42:43], v[2:5], off offset:2048
	v_add_f32_e32 v6, v36, v14
	v_add_f32_e32 v7, v36, v15
	v_add_f32_e32 v2, v36, v10
	v_add_f32_e32 v3, v36, v11
	s_nop 0
	v_permlane32_swap_b32_e32 v2, v6
	v_permlane32_swap_b32_e32 v3, v7
	s_waitcnt vmcnt(14)
	v_lshlrev_b32_e32 v4, 16, v22
	v_and_b32_e32 v5, 0xffff0000, v22
	v_pk_mul_f32 v[2:3], v[4:5], v[2:3]
	s_waitcnt vmcnt(13)
	v_lshlrev_b32_e32 v4, 16, v18
	v_and_b32_e32 v5, 0xffff0000, v18
	v_add_f32_e32 v10, v36, v12
	v_add_f32_e32 v12, v36, v16
	v_add_f32_e32 v11, v36, v13
	v_add_f32_e32 v13, v36, v17
	v_pk_mul_f32 v[14:15], v[2:3], v[2:3]
	v_pk_mul_f32 v[2:3], v[2:3], v[4:5]
	v_permlane32_swap_b32_e32 v10, v12
	v_permlane32_swap_b32_e32 v11, v13
	v_cvt_pk_bf16_f32 v4, v2, v3
	v_lshlrev_b32_e32 v2, 16, v23
	v_and_b32_e32 v3, 0xffff0000, v23
	v_lshlrev_b32_e32 v16, 16, v19
	v_pk_mul_f32 v[2:3], v[2:3], v[10:11]
	v_and_b32_e32 v17, 0xffff0000, v19
	v_pk_mul_f32 v[10:11], v[2:3], v[2:3]
	v_pk_mul_f32 v[2:3], v[2:3], v[16:17]
	s_lshl_b32 s16, s33, 1
	v_cvt_pk_bf16_f32 v5, v2, v3
	v_lshlrev_b32_e32 v2, 16, v24
	v_and_b32_e32 v3, 0xffff0000, v24
	v_pk_mul_f32 v[2:3], v[2:3], v[6:7]
	v_lshlrev_b32_e32 v6, 16, v20
	v_and_b32_e32 v7, 0xffff0000, v20
	v_pk_mul_f32 v[16:17], v[2:3], v[2:3]
	v_pk_mul_f32 v[2:3], v[2:3], v[6:7]
	v_add_f32_e32 v7, v8, v9
	v_cvt_pk_bf16_f32 v6, v2, v3
	v_lshlrev_b32_e32 v2, 16, v25
	v_and_b32_e32 v3, 0xffff0000, v25
	v_pk_mul_f32 v[12:13], v[2:3], v[12:13]
	v_add_f32_e32 v8, v26, v27
	v_pk_mul_f32 v[2:3], v[12:13], v[12:13]
	v_add_f32_e32 v7, v8, v7
	v_add_f32_e32 v8, v30, v31
	v_add_f32_e32 v9, v40, v41
	v_add_f32_e32 v8, v9, v8
	v_add_f32_e32 v2, v2, v3
	v_add_f32_e32 v3, v16, v17
	v_add_f32_e32 v7, v8, v7
	v_add_f32_e32 v2, v3, v2
	v_add_f32_e32 v3, v10, v11
	v_add_f32_e32 v8, v14, v15
	v_add_f32_e32 v3, v8, v3
	v_add_f32_e32 v2, v3, v2
	v_xor_b32_e32 v3, 32, v185
	v_cmp_lt_i32_e32 vcc, v3, v186
	v_add_f32_e32 v2, v7, v2
	s_ashr_i32 s17, s16, 31
	v_cndmask_b32_e32 v3, v185, v3, vcc
	v_lshlrev_b32_e32 v40, 2, v3
	ds_bpermute_b32 v3, v40, v2
	s_lshl_b64 s[16:17], s[16:17], 2
	v_readlane_b32 s4, v253, 41
	v_lshlrev_b32_e32 v8, 16, v21
	v_and_b32_e32 v9, 0xffff0000, v21
	s_add_u32 s16, s4, s16
	v_readlane_b32 s4, v253, 44
	v_pk_mul_f32 v[8:9], v[12:13], v[8:9]
	s_addc_u32 s17, s4, s17
	v_cvt_pk_bf16_f32 v7, v8, v9
	global_store_dwordx4 v[42:43], v[4:7], off offset:2080
	s_and_saveexec_b64 s[18:19], s[40:41]
	s_cbranch_execz .LBB0_492
	v_lshlrev_b64 v[4:5], 7, v[0:1]
	v_lshl_add_u64 v[4:5], s[16:17], 0, v[4:5]
	s_waitcnt lgkmcnt(0)
	v_add_f32_e32 v0, v2, v3
	global_store_dword v[4:5], v0, off
.LBB0_492:
	s_or_b64 exec, exec, s[18:19]
	v_add_u32_e32 v0, s14, v38
	s_waitcnt lgkmcnt(0)
	v_mov_b64_e32 v[2:3], s[68:69]
	v_mad_u64_u32 v[2:3], s[14:15], v0, s73, v[2:3]
	v_lshl_add_u64 v[2:3], s[0:1], 1, v[2:3]
	v_lshl_add_u64 v[2:3], v[2:3], 0, s[44:45]
	v_lshl_add_u64 v[2:3], v[34:35], 1, v[2:3]
	s_mov_b64 s[4:5], 0x1400
	v_add_co_u32_e32 v8, vcc, 0x1000, v2
	v_lshl_add_u64 v[4:5], v[2:3], 0, s[4:5]
	s_mov_b64 s[4:5], 0x2400
	v_addc_co_u32_e32 v9, vcc, 0, v3, vcc
	v_lshl_add_u64 v[6:7], v[2:3], 0, s[4:5]
	v_add_co_u32_e32 v2, vcc, 0x2000, v2
	v_readlane_b32 s4, v254, 56
	s_nop 0
	v_addc_co_u32_e32 v3, vcc, 0, v3, vcc
	v_mov_b32_e32 v2, 0
	v_add_u32_e32 v41, s4, v39
	v_mov_b32_e32 v42, v37
	s_mov_b32 s11, s77
	v_mov_b32_e32 v3, v2
	v_mov_b32_e32 v4, v2
	v_mov_b32_e32 v5, v2
	v_mov_b32_e32 v6, v2
	v_mov_b32_e32 v7, v2
	v_mov_b32_e32 v8, v2
	v_mov_b32_e32 v9, v2
	v_mov_b32_e32 v10, v2
	v_mov_b32_e32 v11, v2
	v_mov_b32_e32 v12, v2
	v_mov_b32_e32 v13, v2
	v_mov_b32_e32 v14, v2
	v_mov_b32_e32 v15, v2
	v_mov_b32_e32 v16, v2
	v_mov_b32_e32 v17, v2
	v_add_u32_e32 v43, 0xfffffdc0, v41
	ds_read_b64_tr_b16 v[44:45], v43
	ds_read_b64_tr_b16 v[46:47], v43 offset:576
	ds_read_b128 v[48:51], v42
; #define LAS __attribute__((address_space(3)))
; __device__ __forceinline__ unsigned pk2(float lo, float hi) { const f32x2 v = {lo, hi}; return __builtin_bit_cast(unsigned, __builtin_convertvector(v, bf16x2_t)); }
; #define MFMA32(a, b, c) __builtin_amdgcn_mfma_f32_32x32x16_bf16((a), (b), (c), 0, 0, 0)
; __device__ __forceinline__ void gmlp_task(LAS unsigned char* lds, const Params& p, const bf16_t* P, bf16_t* Y, const float* svg, float* ssb, int l, bool sample, int b, int g, int q, int tid, int wave, int lane, bool load_ws = true) {
;     ...
;             for (int ks = 0; ks < nks; ++ks) {
;                 const s16x4 alo = __builtin_amdgcn_ds_read_tr16_b64_v4i16((LAS s16x4*)(tr + 16 * ks * 72)), ahi = __builtin_amdgcn_ds_read_tr16_b64_v4i16((LAS s16x4*)(tr + (16 * ks + 4) * 72));
;                 const bf16x8 a = __builtin_shufflevector(alo, ahi, 0, 1, 2, 3, 4, 5, 6, 7);
;                 const bf16x8 bw = *(const LAS bf16x8*)(WSL + (32 * it + r) * 136 + 16 * ks + 8 * h);
;                 acc = MFMA32(a, bw, acc);
;             }
;             bf16_t* yp = Y + row * DM + 1024 + g * 64 + 32 * dt + 8 * h;
;             float ss = 0.f;
; #pragma unroll
;             for (int pr = 0; pr < 2; ++pr) {
;                 float a[4], bq[4];
; #pragma unroll
;                 for (int k = 0; k < 4; ++k) { a[k] = acc[8 * pr + k] + bias; bq[k] = acc[8 * pr + 4 + k] + bias; }
; #pragma unroll
;                 for (int k = 0; k < 4; ++k) swap_halves(a[k], bq[k]);
;                 const u32x4 u4 = uw[pr], g4 = gw[pr];
;                 a[0] *= bf_lo(u4.x); a[1] *= bf_hi(u4.x); a[2] *= bf_lo(u4.y); a[3] *= bf_hi(u4.y); bq[0] *= bf_lo(u4.z); bq[1] *= bf_hi(u4.z); bq[2] *= bf_lo(u4.w); bq[3] *= bf_hi(u4.w);
;                 ss += ((a[0] * a[0] + a[1] * a[1]) + (a[2] * a[2] + a[3] * a[3])) + ((bq[0] * bq[0] + bq[1] * bq[1]) + (bq[2] * bq[2] + bq[3] * bq[3]));
;                 u32x4 w; w.x = pk2(a[0] * bf_lo(g4.x), a[1] * bf_hi(g4.x)); w.y = pk2(a[2] * bf_lo(g4.y), a[3] * bf_hi(g4.y));
;                 w.z = pk2(bq[0] * bf_lo(g4.z), bq[1] * bf_hi(g4.z)); w.w = pk2(bq[2] * bf_lo(g4.w), bq[3] * bf_hi(g4.w));
;                 *(u32x4*)(yp + 16 * pr) = w;
;             }
;             ss += __shfl_xor(ss, 32);
;             if (h == 0) ssb[row * 32 + g * 2 + dt] = ss;
.Lmy_c493_loop:
	ds_read_b64_tr_b16 v[116:117], v43 offset:2304
	ds_read_b64_tr_b16 v[118:119], v43 offset:2880
	ds_read_b128 v[120:123], v42 offset:32
	s_add_i32 s11, s11, -2
	v_add_u32_e32 v42, 64, v42
	v_add_u32_e32 v43, 0x1200, v43
	s_cmp_eq_u32 s11, 0
	s_waitcnt lgkmcnt(3)
	v_mfma_f32_32x32x16_bf16 v[2:17], v[44:47], v[48:51], v[2:17]
	s_cbranch_scc1 .Lmy_c493_tail
	ds_read_b64_tr_b16 v[44:45], v43
	ds_read_b64_tr_b16 v[46:47], v43 offset:576
	ds_read_b128 v[48:51], v42
	s_waitcnt lgkmcnt(3)
	v_mfma_f32_32x32x16_bf16 v[2:17], v[116:119], v[120:123], v[2:17]
	s_branch .Lmy_c493_loop
.Lmy_c493_tail:
	s_waitcnt lgkmcnt(0)
	v_mfma_f32_32x32x16_bf16 v[2:17], v[116:119], v[120:123], v[2:17]
	s_nop 10
	v_add_f32_e32 v2, v36, v2
	v_add_f32_e32 v6, v36, v6
	v_add_f32_e32 v3, v36, v3
	v_add_f32_e32 v7, v36, v7
	v_add_f32_e32 v4, v36, v4
	v_add_f32_e32 v8, v36, v8
	v_add_f32_e32 v5, v36, v5
	v_add_f32_e32 v9, v36, v9
	v_permlane32_swap_b32_e32 v2, v6
	v_permlane32_swap_b32_e32 v3, v7
	v_permlane32_swap_b32_e32 v4, v8
	v_permlane32_swap_b32_e32 v5, v9
	s_waitcnt vmcnt(14)
	v_lshlrev_b32_e32 v44, 16, v80
	v_and_b32_e32 v45, 0xffff0000, v80
	v_lshlrev_b32_e32 v30, 16, v81
	v_and_b32_e32 v31, 0xffff0000, v81
	v_pk_mul_f32 v[2:3], v[44:45], v[2:3]
	s_waitcnt vmcnt(13)
	v_lshlrev_b32_e32 v46, 16, v76
	v_and_b32_e32 v47, 0xffff0000, v76
	v_pk_mul_f32 v[4:5], v[30:31], v[4:5]
	v_lshlrev_b32_e32 v26, 16, v77
	v_and_b32_e32 v27, 0xffff0000, v77
	v_pk_mul_f32 v[44:45], v[2:3], v[2:3]
	v_pk_mul_f32 v[2:3], v[2:3], v[46:47]
	v_pk_mul_f32 v[30:31], v[4:5], v[4:5]
	v_pk_mul_f32 v[4:5], v[4:5], v[26:27]
	v_cvt_pk_bf16_f32 v2, v2, v3
	v_cvt_pk_bf16_f32 v3, v4, v5
	v_lshlrev_b32_e32 v4, 16, v82
	v_and_b32_e32 v5, 0xffff0000, v82
	v_lshlrev_b64 v[42:43], 12, v[0:1]
	v_pk_mul_f32 v[4:5], v[4:5], v[6:7]
	v_lshlrev_b32_e32 v6, 16, v78
	v_and_b32_e32 v7, 0xffff0000, v78
	v_lshl_add_u64 v[42:43], s[36:37], 0, v[42:43]
	v_pk_mul_f32 v[26:27], v[4:5], v[4:5]
	v_pk_mul_f32 v[4:5], v[4:5], v[6:7]
	v_lshlrev_b32_e32 v6, 16, v83
	v_and_b32_e32 v7, 0xffff0000, v83
	v_lshl_add_u64 v[42:43], s[0:1], 1, v[42:43]
	v_pk_mul_f32 v[6:7], v[6:7], v[8:9]
	v_lshlrev_b32_e32 v28, 16, v79
	v_and_b32_e32 v29, 0xffff0000, v79
	v_lshl_add_u64 v[42:43], v[42:43], 0, s[44:45]
	v_pk_mul_f32 v[8:9], v[6:7], v[6:7]
	v_pk_mul_f32 v[6:7], v[6:7], v[28:29]
	v_lshl_add_u64 v[42:43], v[34:35], 1, v[42:43]
	v_cvt_pk_bf16_f32 v4, v4, v5
	v_cvt_pk_bf16_f32 v5, v6, v7
	global_store_dwordx4 v[42:43], v[2:5], off offset:2048
	v_add_f32_e32 v6, v36, v14
	v_add_f32_e32 v7, v36, v15
	v_add_f32_e32 v2, v36, v10
	v_add_f32_e32 v3, v36, v11
	s_nop 0
	v_permlane32_swap_b32_e32 v2, v6
	v_permlane32_swap_b32_e32 v3, v7
	s_waitcnt vmcnt(13)
	v_lshlrev_b32_e32 v4, 16, v72
	v_and_b32_e32 v5, 0xffff0000, v72
	v_pk_mul_f32 v[2:3], v[4:5], v[2:3]
	s_waitcnt vmcnt(12)
	v_lshlrev_b32_e32 v4, 16, v68
	v_and_b32_e32 v5, 0xffff0000, v68
	v_add_f32_e32 v10, v36, v12
	v_add_f32_e32 v12, v36, v16
	v_add_f32_e32 v11, v36, v13
	v_add_f32_e32 v13, v36, v17
	v_pk_mul_f32 v[14:15], v[2:3], v[2:3]
	v_pk_mul_f32 v[2:3], v[2:3], v[4:5]
	v_permlane32_swap_b32_e32 v10, v12
	v_permlane32_swap_b32_e32 v11, v13
	v_cvt_pk_bf16_f32 v4, v2, v3
	v_lshlrev_b32_e32 v2, 16, v73
	v_and_b32_e32 v3, 0xffff0000, v73
	v_lshlrev_b32_e32 v16, 16, v69
	v_pk_mul_f32 v[2:3], v[2:3], v[10:11]
	v_and_b32_e32 v17, 0xffff0000, v69
	v_pk_mul_f32 v[10:11], v[2:3], v[2:3]
	v_pk_mul_f32 v[2:3], v[2:3], v[16:17]
	s_nop 0
	v_cvt_pk_bf16_f32 v5, v2, v3
	v_lshlrev_b32_e32 v2, 16, v74
	v_and_b32_e32 v3, 0xffff0000, v74
	v_pk_mul_f32 v[2:3], v[2:3], v[6:7]
	v_lshlrev_b32_e32 v6, 16, v70
	v_and_b32_e32 v7, 0xffff0000, v70
	v_pk_mul_f32 v[16:17], v[2:3], v[2:3]
	v_pk_mul_f32 v[2:3], v[2:3], v[6:7]
	v_add_f32_e32 v7, v8, v9
	v_cvt_pk_bf16_f32 v6, v2, v3
	v_lshlrev_b32_e32 v2, 16, v75
	v_and_b32_e32 v3, 0xffff0000, v75
	v_pk_mul_f32 v[12:13], v[2:3], v[12:13]
	v_add_f32_e32 v8, v26, v27
	v_pk_mul_f32 v[2:3], v[12:13], v[12:13]
	v_add_f32_e32 v7, v8, v7
	v_add_f32_e32 v8, v30, v31
	v_add_f32_e32 v9, v44, v45
	v_add_f32_e32 v8, v9, v8
	v_add_f32_e32 v2, v2, v3
	v_add_f32_e32 v3, v16, v17
	v_add_f32_e32 v7, v8, v7
	v_add_f32_e32 v2, v3, v2
	v_add_f32_e32 v3, v10, v11
	v_add_f32_e32 v8, v14, v15
	v_add_f32_e32 v3, v8, v3
	v_add_f32_e32 v2, v3, v2
	v_add_f32_e32 v2, v7, v2
	ds_bpermute_b32 v3, v40, v2
	v_lshlrev_b32_e32 v8, 16, v71
	v_and_b32_e32 v9, 0xffff0000, v71
	v_pk_mul_f32 v[8:9], v[12:13], v[8:9]
	s_nop 0
	v_cvt_pk_bf16_f32 v7, v8, v9
	global_store_dwordx4 v[42:43], v[4:7], off offset:2080
	s_and_saveexec_b64 s[14:15], s[40:41]
	s_cbranch_execz .LBB0_496
	v_lshlrev_b64 v[4:5], 7, v[0:1]
	v_lshl_add_u64 v[4:5], s[16:17], 0, v[4:5]
	s_waitcnt lgkmcnt(0)
	v_add_f32_e32 v0, v2, v3
	global_store_dword v[4:5], v0, off
.LBB0_496:
	s_or_b64 exec, exec, s[14:15]
	v_add_u32_e32 v0, s12, v38
	s_waitcnt lgkmcnt(0)
	v_mov_b64_e32 v[2:3], s[68:69]
	v_mad_u64_u32 v[2:3], s[12:13], v0, s73, v[2:3]
	v_lshl_add_u64 v[2:3], s[0:1], 1, v[2:3]
	v_lshl_add_u64 v[2:3], v[2:3], 0, s[44:45]
	v_lshl_add_u64 v[2:3], v[34:35], 1, v[2:3]
	s_mov_b64 s[4:5], 0x1400
	v_add_co_u32_e32 v8, vcc, 0x1000, v2
	v_lshl_add_u64 v[4:5], v[2:3], 0, s[4:5]
	s_mov_b64 s[4:5], 0x2400
	v_addc_co_u32_e32 v9, vcc, 0, v3, vcc
	v_lshl_add_u64 v[6:7], v[2:3], 0, s[4:5]
	v_add_co_u32_e32 v2, vcc, 0x2000, v2
	v_readlane_b32 s4, v254, 57
	s_nop 0
	v_addc_co_u32_e32 v3, vcc, 0, v3, vcc
	v_mov_b32_e32 v2, 0
	v_add_u32_e32 v41, s4, v39
	v_mov_b32_e32 v42, v37
	s_mov_b32 s11, s77
	v_mov_b32_e32 v3, v2
	v_mov_b32_e32 v4, v2
	v_mov_b32_e32 v5, v2
	v_mov_b32_e32 v6, v2
	v_mov_b32_e32 v7, v2
	v_mov_b32_e32 v8, v2
	v_mov_b32_e32 v9, v2
	v_mov_b32_e32 v10, v2
	v_mov_b32_e32 v11, v2
	v_mov_b32_e32 v12, v2
	v_mov_b32_e32 v13, v2
	v_mov_b32_e32 v14, v2
	v_mov_b32_e32 v15, v2
	v_mov_b32_e32 v16, v2
	v_mov_b32_e32 v17, v2
	v_add_u32_e32 v43, 0xfffffdc0, v41
	ds_read_b64_tr_b16 v[44:45], v43
	ds_read_b64_tr_b16 v[46:47], v43 offset:576
	ds_read_b128 v[48:51], v42

; #define LAS __attribute__((address_space(3)))
; __device__ __forceinline__ unsigned pk2(float lo, float hi) { const f32x2 v = {lo, hi}; return __builtin_bit_cast(unsigned, __builtin_convertvector(v, bf16x2_t)); }
; __device__ __forceinline__ void gmlp_task(LAS unsigned char* lds, const Params& p, const bf16_t* P, bf16_t* Y, const float* svg, float* ssb, int l, bool sample, int b, int g, int q, int tid, int wave, int lane, bool load_ws = true) {
;     ...
; #pragma unroll
;             for (int pr = 0; pr < 2; ++pr) { uw[pr] = *(const u32x4*)(up + 16 * pr); gw[pr] = *(const u32x4*)(gp + 16 * pr); }
;             f32x16 acc;
; #pragma unroll
;             for (int e = 0; e < 16; ++e) acc[e] = 0.f;
;             const LAS bf16_t* tr = VGT + (8 * h + ((lane & 15) >> 2)) * 72 + 32 * dt + 16 * ((lane >> 4) & 1) + 4 * (lane & 3);
;             for (int ks = 0; ks < nks; ++ks) {
;                 const s16x4 alo = __builtin_amdgcn_ds_read_tr16_b64_v4i16((LAS s16x4*)(tr + 16 * ks * 72)), ahi = __builtin_amdgcn_ds_read_tr16_b64_v4i16((LAS s16x4*)(tr + (16 * ks + 4) * 72));
;     ...
;             bf16_t* yp = Y + row * DM + 1024 + g * 64 + 32 * dt + 8 * h;
;             float ss = 0.f;
; #pragma unroll
;             for (int pr = 0; pr < 2; ++pr) {
;                 float a[4], bq[4];
; #pragma unroll
;                 for (int k = 0; k < 4; ++k) { a[k] = acc[8 * pr + k] + bias; bq[k] = acc[8 * pr + 4 + k] + bias; }
; #pragma unroll
;                 for (int k = 0; k < 4; ++k) swap_halves(a[k], bq[k]);
;                 const u32x4 u4 = uw[pr], g4 = gw[pr];
;                 a[0] *= bf_lo(u4.x); a[1] *= bf_hi(u4.x); a[2] *= bf_lo(u4.y); a[3] *= bf_hi(u4.y); bq[0] *= bf_lo(u4.z); bq[1] *= bf_hi(u4.z); bq[2] *= bf_lo(u4.w); bq[3] *= bf_hi(u4.w);
;                 ss += ((a[0] * a[0] + a[1] * a[1]) + (a[2] * a[2] + a[3] * a[3])) + ((bq[0] * bq[0] + bq[1] * bq[1]) + (bq[2] * bq[2] + bq[3] * bq[3]));
;                 u32x4 w; w.x = pk2(a[0] * bf_lo(g4.x), a[1] * bf_hi(g4.x)); w.y = pk2(a[2] * bf_lo(g4.y), a[3] * bf_hi(g4.y));
;                 w.z = pk2(bq[0] * bf_lo(g4.z), bq[1] * bf_hi(g4.z)); w.w = pk2(bq[2] * bf_lo(g4.w), bq[3] * bf_hi(g4.w));
;                 *(u32x4*)(yp + 16 * pr) = w;
;             }
;             ss += __shfl_xor(ss, 32);
;             if (h == 0) ssb[row * 32 + g * 2 + dt] = ss;
.Lmy_c497_tail:
	s_waitcnt lgkmcnt(0)
	v_mfma_f32_32x32x16_bf16 v[2:17], v[116:119], v[120:123], v[2:17]
	s_nop 10
	v_add_f32_e32 v2, v36, v2
	v_add_f32_e32 v6, v36, v6
	v_add_f32_e32 v3, v36, v3
	v_add_f32_e32 v7, v36, v7
	v_add_f32_e32 v4, v36, v4
	v_add_f32_e32 v8, v36, v8
	v_add_f32_e32 v5, v36, v5
	v_add_f32_e32 v9, v36, v9
	v_permlane32_swap_b32_e32 v2, v6
	v_permlane32_swap_b32_e32 v3, v7
	v_permlane32_swap_b32_e32 v4, v8
	v_permlane32_swap_b32_e32 v5, v9
	s_waitcnt vmcnt(13)
	v_lshlrev_b32_e32 v44, 16, v96
	v_and_b32_e32 v45, 0xffff0000, v96
	v_lshlrev_b32_e32 v30, 16, v97
	v_and_b32_e32 v31, 0xffff0000, v97
	v_pk_mul_f32 v[2:3], v[44:45], v[2:3]
	s_waitcnt vmcnt(12)
	v_lshlrev_b32_e32 v46, 16, v92
	v_and_b32_e32 v47, 0xffff0000, v92
	v_pk_mul_f32 v[4:5], v[30:31], v[4:5]
	v_lshlrev_b32_e32 v26, 16, v93
	v_and_b32_e32 v27, 0xffff0000, v93
	v_pk_mul_f32 v[44:45], v[2:3], v[2:3]
	v_pk_mul_f32 v[2:3], v[2:3], v[46:47]
	v_pk_mul_f32 v[30:31], v[4:5], v[4:5]
	v_pk_mul_f32 v[4:5], v[4:5], v[26:27]
	v_cvt_pk_bf16_f32 v2, v2, v3
	v_cvt_pk_bf16_f32 v3, v4, v5
	v_lshlrev_b32_e32 v4, 16, v98
	v_and_b32_e32 v5, 0xffff0000, v98
	v_lshlrev_b64 v[42:43], 12, v[0:1]
	v_pk_mul_f32 v[4:5], v[4:5], v[6:7]
	v_lshlrev_b32_e32 v6, 16, v94
	v_and_b32_e32 v7, 0xffff0000, v94
	v_lshl_add_u64 v[42:43], s[36:37], 0, v[42:43]
	v_pk_mul_f32 v[26:27], v[4:5], v[4:5]
	v_pk_mul_f32 v[4:5], v[4:5], v[6:7]
	v_lshlrev_b32_e32 v6, 16, v99
	v_and_b32_e32 v7, 0xffff0000, v99
	v_lshl_add_u64 v[42:43], s[0:1], 1, v[42:43]
	v_pk_mul_f32 v[6:7], v[6:7], v[8:9]
	v_lshlrev_b32_e32 v28, 16, v95
	v_and_b32_e32 v29, 0xffff0000, v95
	v_lshl_add_u64 v[42:43], v[42:43], 0, s[44:45]
	v_pk_mul_f32 v[8:9], v[6:7], v[6:7]
	v_pk_mul_f32 v[6:7], v[6:7], v[28:29]
	v_lshl_add_u64 v[42:43], v[34:35], 1, v[42:43]
	v_cvt_pk_bf16_f32 v4, v4, v5
	v_cvt_pk_bf16_f32 v5, v6, v7
	global_store_dwordx4 v[42:43], v[2:5], off offset:2048
	v_add_f32_e32 v6, v36, v14
	v_add_f32_e32 v7, v36, v15
	v_add_f32_e32 v2, v36, v10
	v_add_f32_e32 v3, v36, v11
	s_nop 0
	v_permlane32_swap_b32_e32 v2, v6
	v_permlane32_swap_b32_e32 v3, v7
	s_waitcnt vmcnt(12)
	v_lshlrev_b32_e32 v4, 16, v88
	v_and_b32_e32 v5, 0xffff0000, v88
	v_pk_mul_f32 v[2:3], v[4:5], v[2:3]
	s_waitcnt vmcnt(11)
	v_lshlrev_b32_e32 v4, 16, v84
	v_and_b32_e32 v5, 0xffff0000, v84
	v_add_f32_e32 v10, v36, v12
	v_add_f32_e32 v12, v36, v16
	v_add_f32_e32 v11, v36, v13
	v_add_f32_e32 v13, v36, v17
	v_pk_mul_f32 v[14:15], v[2:3], v[2:3]
	v_pk_mul_f32 v[2:3], v[2:3], v[4:5]
	v_permlane32_swap_b32_e32 v10, v12
	v_permlane32_swap_b32_e32 v11, v13
	v_cvt_pk_bf16_f32 v4, v2, v3
	v_lshlrev_b32_e32 v2, 16, v89
	v_and_b32_e32 v3, 0xffff0000, v89
	v_lshlrev_b32_e32 v16, 16, v85
	v_pk_mul_f32 v[2:3], v[2:3], v[10:11]
	v_and_b32_e32 v17, 0xffff0000, v85
	v_pk_mul_f32 v[10:11], v[2:3], v[2:3]
	v_pk_mul_f32 v[2:3], v[2:3], v[16:17]
	s_nop 0
	v_cvt_pk_bf16_f32 v5, v2, v3
	v_lshlrev_b32_e32 v2, 16, v90
	v_and_b32_e32 v3, 0xffff0000, v90
	v_pk_mul_f32 v[2:3], v[2:3], v[6:7]
	v_lshlrev_b32_e32 v6, 16, v86
	v_and_b32_e32 v7, 0xffff0000, v86
	v_pk_mul_f32 v[16:17], v[2:3], v[2:3]
	v_pk_mul_f32 v[2:3], v[2:3], v[6:7]
	v_add_f32_e32 v7, v8, v9
	v_cvt_pk_bf16_f32 v6, v2, v3
	v_lshlrev_b32_e32 v2, 16, v91
	v_and_b32_e32 v3, 0xffff0000, v91
	v_pk_mul_f32 v[12:13], v[2:3], v[12:13]
	v_add_f32_e32 v8, v26, v27
	v_pk_mul_f32 v[2:3], v[12:13], v[12:13]
	v_add_f32_e32 v7, v8, v7
	v_add_f32_e32 v8, v30, v31
	v_add_f32_e32 v9, v44, v45
	v_add_f32_e32 v8, v9, v8
	v_add_f32_e32 v2, v2, v3
	v_add_f32_e32 v3, v16, v17
	v_add_f32_e32 v7, v8, v7
	v_add_f32_e32 v2, v3, v2
	v_add_f32_e32 v3, v10, v11
	v_add_f32_e32 v8, v14, v15
	v_add_f32_e32 v3, v8, v3
	v_add_f32_e32 v2, v3, v2
	v_add_f32_e32 v2, v7, v2
	ds_bpermute_b32 v3, v40, v2
	v_lshlrev_b32_e32 v8, 16, v87
	v_and_b32_e32 v9, 0xffff0000, v87
	v_pk_mul_f32 v[8:9], v[12:13], v[8:9]
	s_nop 0
	v_cvt_pk_bf16_f32 v7, v8, v9
	global_store_dwordx4 v[42:43], v[4:7], off offset:2080
	s_and_saveexec_b64 s[12:13], s[40:41]
	s_cbranch_execz .LBB0_500
	v_lshlrev_b64 v[4:5], 7, v[0:1]
	v_lshl_add_u64 v[4:5], s[16:17], 0, v[4:5]
	s_waitcnt lgkmcnt(0)
	v_add_f32_e32 v0, v2, v3
	global_store_dword v[4:5], v0, off
.LBB0_500:
	s_or_b64 exec, exec, s[12:13]
	v_add_u32_e32 v0, s10, v38
	s_waitcnt lgkmcnt(0)
	v_mov_b64_e32 v[2:3], s[68:69]
	v_mad_u64_u32 v[2:3], s[10:11], v0, s73, v[2:3]
	v_lshl_add_u64 v[2:3], s[0:1], 1, v[2:3]
	v_lshl_add_u64 v[2:3], v[2:3], 0, s[44:45]
	v_lshl_add_u64 v[2:3], v[34:35], 1, v[2:3]
	s_mov_b64 s[4:5], 0x1400
	v_add_co_u32_e32 v8, vcc, 0x1000, v2
	v_lshl_add_u64 v[4:5], v[2:3], 0, s[4:5]
	s_mov_b64 s[4:5], 0x2400
	v_addc_co_u32_e32 v9, vcc, 0, v3, vcc
	v_lshl_add_u64 v[6:7], v[2:3], 0, s[4:5]
	v_add_co_u32_e32 v2, vcc, 0x2000, v2
	v_readlane_b32 s4, v254, 59
	s_nop 0
	v_addc_co_u32_e32 v3, vcc, 0, v3, vcc
	v_mov_b32_e32 v2, 0
	v_add_u32_e32 v38, s4, v39
	s_mov_b32 s10, s77
	v_mov_b32_e32 v3, v2
	v_mov_b32_e32 v4, v2
	v_mov_b32_e32 v5, v2
	v_mov_b32_e32 v6, v2
	v_mov_b32_e32 v7, v2
	v_mov_b32_e32 v8, v2
	v_mov_b32_e32 v9, v2
	v_mov_b32_e32 v10, v2
	v_mov_b32_e32 v11, v2
	v_mov_b32_e32 v12, v2
	v_mov_b32_e32 v13, v2
	v_mov_b32_e32 v14, v2
	v_mov_b32_e32 v15, v2
	v_mov_b32_e32 v16, v2
	v_mov_b32_e32 v17, v2
	v_add_u32_e32 v39, 0xfffffdc0, v38
	ds_read_b64_tr_b16 v[42:43], v39
	ds_read_b64_tr_b16 v[44:45], v39 offset:576
	ds_read_b128 v[46:49], v37
; #define LAS __attribute__((address_space(3)))
; __device__ __forceinline__ unsigned pk2(float lo, float hi) { const f32x2 v = {lo, hi}; return __builtin_bit_cast(unsigned, __builtin_convertvector(v, bf16x2_t)); }
; #define MFMA32(a, b, c) __builtin_amdgcn_mfma_f32_32x32x16_bf16((a), (b), (c), 0, 0, 0)
; __device__ __forceinline__ void gmlp_task(LAS unsigned char* lds, const Params& p, const bf16_t* P, bf16_t* Y, const float* svg, float* ssb, int l, bool sample, int b, int g, int q, int tid, int wave, int lane, bool load_ws = true) {
;     ...
;             for (int ks = 0; ks < nks; ++ks) {
;                 const s16x4 alo = __builtin_amdgcn_ds_read_tr16_b64_v4i16((LAS s16x4*)(tr + 16 * ks * 72)), ahi = __builtin_amdgcn_ds_read_tr16_b64_v4i16((LAS s16x4*)(tr + (16 * ks + 4) * 72));
;                 const bf16x8 a = __builtin_shufflevector(alo, ahi, 0, 1, 2, 3, 4, 5, 6, 7);
;                 const bf16x8 bw = *(const LAS bf16x8*)(WSL + (32 * it + r) * 136 + 16 * ks + 8 * h);
;                 acc = MFMA32(a, bw, acc);
;             }
;             bf16_t* yp = Y + row * DM + 1024 + g * 64 + 32 * dt + 8 * h;
;             float ss = 0.f;
; #pragma unroll
;             for (int pr = 0; pr < 2; ++pr) {
;                 float a[4], bq[4];
; #pragma unroll
;                 for (int k = 0; k < 4; ++k) { a[k] = acc[8 * pr + k] + bias; bq[k] = acc[8 * pr + 4 + k] + bias; }
; #pragma unroll
;                 for (int k = 0; k < 4; ++k) swap_halves(a[k], bq[k]);
;                 const u32x4 u4 = uw[pr], g4 = gw[pr];
;                 a[0] *= bf_lo(u4.x); a[1] *= bf_hi(u4.x); a[2] *= bf_lo(u4.y); a[3] *= bf_hi(u4.y); bq[0] *= bf_lo(u4.z); bq[1] *= bf_hi(u4.z); bq[2] *= bf_lo(u4.w); bq[3] *= bf_hi(u4.w);
;                 ss += ((a[0] * a[0] + a[1] * a[1]) + (a[2] * a[2] + a[3] * a[3])) + ((bq[0] * bq[0] + bq[1] * bq[1]) + (bq[2] * bq[2] + bq[3] * bq[3]));
;                 u32x4 w; w.x = pk2(a[0] * bf_lo(g4.x), a[1] * bf_hi(g4.x)); w.y = pk2(a[2] * bf_lo(g4.y), a[3] * bf_hi(g4.y));
;                 w.z = pk2(bq[0] * bf_lo(g4.z), bq[1] * bf_hi(g4.z)); w.w = pk2(bq[2] * bf_lo(g4.w), bq[3] * bf_hi(g4.w));
;                 *(u32x4*)(yp + 16 * pr) = w;
;             }
;             ss += __shfl_xor(ss, 32);
;             if (h == 0) ssb[row * 32 + g * 2 + dt] = ss;
.Lmy_c501_loop:
	ds_read_b64_tr_b16 v[116:117], v39 offset:2304
	ds_read_b64_tr_b16 v[118:119], v39 offset:2880
	ds_read_b128 v[120:123], v37 offset:32
	s_add_i32 s10, s10, -2
	v_add_u32_e32 v37, 64, v37
	v_add_u32_e32 v39, 0x1200, v39
	s_cmp_eq_u32 s10, 0
	s_waitcnt lgkmcnt(3)
	v_mfma_f32_32x32x16_bf16 v[2:17], v[42:45], v[46:49], v[2:17]
	s_cbranch_scc1 .Lmy_c501_tail
	ds_read_b64_tr_b16 v[42:43], v39
	ds_read_b64_tr_b16 v[44:45], v39 offset:576
	ds_read_b128 v[46:49], v37
	s_waitcnt lgkmcnt(3)
	v_mfma_f32_32x32x16_bf16 v[2:17], v[116:119], v[120:123], v[2:17]
	s_branch .Lmy_c501_loop
.Lmy_c501_tail:
	s_waitcnt lgkmcnt(0)
	v_mfma_f32_32x32x16_bf16 v[2:17], v[116:119], v[120:123], v[2:17]
	v_lshlrev_b64 v[38:39], 12, v[0:1]
	v_lshl_add_u64 v[38:39], s[36:37], 0, v[38:39]
	v_lshl_add_u64 v[38:39], s[0:1], 1, v[38:39]
	s_nop 7
	v_add_f32_e32 v2, v36, v2
	v_add_f32_e32 v6, v36, v6
	v_add_f32_e32 v3, v36, v3
	v_add_f32_e32 v7, v36, v7
	v_add_f32_e32 v4, v36, v4
	v_add_f32_e32 v8, v36, v8
	v_add_f32_e32 v5, v36, v5
	v_add_f32_e32 v9, v36, v9
	v_lshl_add_u64 v[38:39], v[38:39], 0, s[44:45]
	v_permlane32_swap_b32_e32 v2, v6
	v_permlane32_swap_b32_e32 v3, v7
	v_permlane32_swap_b32_e32 v4, v8
	v_permlane32_swap_b32_e32 v5, v9
	v_lshl_add_u64 v[34:35], v[34:35], 1, v[38:39]
	s_waitcnt vmcnt(12)
	v_lshlrev_b32_e32 v38, 16, v112
	v_and_b32_e32 v39, 0xffff0000, v112
	v_lshlrev_b32_e32 v30, 16, v113
	v_and_b32_e32 v31, 0xffff0000, v113
	v_pk_mul_f32 v[2:3], v[38:39], v[2:3]
	s_waitcnt vmcnt(11)
	v_lshlrev_b32_e32 v42, 16, v108
	v_and_b32_e32 v43, 0xffff0000, v108
	v_pk_mul_f32 v[4:5], v[30:31], v[4:5]
	v_lshlrev_b32_e32 v26, 16, v109
	v_and_b32_e32 v27, 0xffff0000, v109
	v_pk_mul_f32 v[38:39], v[2:3], v[2:3]
	v_pk_mul_f32 v[2:3], v[2:3], v[42:43]
	v_pk_mul_f32 v[30:31], v[4:5], v[4:5]
	v_pk_mul_f32 v[4:5], v[4:5], v[26:27]
	v_cvt_pk_bf16_f32 v2, v2, v3
	v_cvt_pk_bf16_f32 v3, v4, v5
	v_lshlrev_b32_e32 v4, 16, v114
	v_and_b32_e32 v5, 0xffff0000, v114
	v_pk_mul_f32 v[4:5], v[4:5], v[6:7]
	v_lshlrev_b32_e32 v6, 16, v110
	v_and_b32_e32 v7, 0xffff0000, v110
	v_pk_mul_f32 v[26:27], v[4:5], v[4:5]
	v_pk_mul_f32 v[4:5], v[4:5], v[6:7]
	v_lshlrev_b32_e32 v6, 16, v115
	v_and_b32_e32 v7, 0xffff0000, v115
	v_pk_mul_f32 v[6:7], v[6:7], v[8:9]
	v_lshlrev_b32_e32 v28, 16, v111
	v_and_b32_e32 v29, 0xffff0000, v111
	v_pk_mul_f32 v[8:9], v[6:7], v[6:7]
	v_pk_mul_f32 v[6:7], v[6:7], v[28:29]
	v_cvt_pk_bf16_f32 v4, v4, v5
	v_cvt_pk_bf16_f32 v5, v6, v7
	global_store_dwordx4 v[34:35], v[2:5], off offset:2048
	v_add_f32_e32 v6, v36, v14
	v_add_f32_e32 v7, v36, v15
	v_add_f32_e32 v2, v36, v10
	v_add_f32_e32 v3, v36, v11
	s_nop 0
	v_permlane32_swap_b32_e32 v2, v6
	v_permlane32_swap_b32_e32 v3, v7
	s_waitcnt vmcnt(11)
	v_lshlrev_b32_e32 v4, 16, v104
	v_and_b32_e32 v5, 0xffff0000, v104
	v_pk_mul_f32 v[2:3], v[4:5], v[2:3]
	s_waitcnt vmcnt(10)
	v_lshlrev_b32_e32 v4, 16, v100
	v_and_b32_e32 v5, 0xffff0000, v100
	v_add_f32_e32 v10, v36, v12
	v_add_f32_e32 v12, v36, v16
	v_add_f32_e32 v11, v36, v13
	v_add_f32_e32 v13, v36, v17
	v_pk_mul_f32 v[14:15], v[2:3], v[2:3]
	v_pk_mul_f32 v[2:3], v[2:3], v[4:5]
	v_permlane32_swap_b32_e32 v10, v12
	v_permlane32_swap_b32_e32 v11, v13
	v_cvt_pk_bf16_f32 v4, v2, v3
	v_lshlrev_b32_e32 v2, 16, v105
	v_and_b32_e32 v3, 0xffff0000, v105
	v_lshlrev_b32_e32 v16, 16, v101
	v_pk_mul_f32 v[2:3], v[2:3], v[10:11]
	v_and_b32_e32 v17, 0xffff0000, v101
	v_pk_mul_f32 v[10:11], v[2:3], v[2:3]
	v_pk_mul_f32 v[2:3], v[2:3], v[16:17]
	s_nop 0
	v_cvt_pk_bf16_f32 v5, v2, v3
	v_lshlrev_b32_e32 v2, 16, v106
	v_and_b32_e32 v3, 0xffff0000, v106
	v_pk_mul_f32 v[2:3], v[2:3], v[6:7]
	v_lshlrev_b32_e32 v6, 16, v102
	v_and_b32_e32 v7, 0xffff0000, v102
	v_pk_mul_f32 v[16:17], v[2:3], v[2:3]
	v_pk_mul_f32 v[2:3], v[2:3], v[6:7]
	v_add_f32_e32 v7, v8, v9
	v_cvt_pk_bf16_f32 v6, v2, v3
	v_lshlrev_b32_e32 v2, 16, v107
	v_and_b32_e32 v3, 0xffff0000, v107
	v_pk_mul_f32 v[12:13], v[2:3], v[12:13]
	v_add_f32_e32 v8, v26, v27
	v_pk_mul_f32 v[2:3], v[12:13], v[12:13]
	v_add_f32_e32 v7, v8, v7
	v_add_f32_e32 v8, v30, v31
	v_add_f32_e32 v9, v38, v39
	v_add_f32_e32 v8, v9, v8
	v_add_f32_e32 v2, v2, v3
	v_add_f32_e32 v3, v16, v17
	v_add_f32_e32 v7, v8, v7
	v_add_f32_e32 v2, v3, v2
	v_add_f32_e32 v3, v10, v11
	v_add_f32_e32 v8, v14, v15
	v_add_f32_e32 v3, v8, v3
	v_add_f32_e32 v2, v3, v2
	v_add_f32_e32 v2, v7, v2
	ds_bpermute_b32 v3, v40, v2
	v_lshlrev_b32_e32 v8, 16, v103
	v_and_b32_e32 v9, 0xffff0000, v103
	v_pk_mul_f32 v[8:9], v[12:13], v[8:9]
	s_nop 0
	v_cvt_pk_bf16_f32 v7, v8, v9
	global_store_dwordx4 v[34:35], v[4:7], off offset:2080
	s_and_saveexec_b64 s[0:1], s[40:41]
	s_cbranch_execz .LBB0_448
	v_lshlrev_b64 v[4:5], 7, v[0:1]
	v_lshl_add_u64 v[4:5], s[16:17], 0, v[4:5]
	s_waitcnt lgkmcnt(0)
	v_add_f32_e32 v0, v2, v3
	global_store_dword v[4:5], v0, off
	s_branch .LBB0_448
